# PB attention: ALiBi key term folded into QK MFMA accumulator input (+K/-K/0 per block), QK chain at iteration tail straight into score registers (no copies), Q/sink hoist, staging de-serialised
# speedup vs baseline: 1.0048x; 1.0048x over previous
; #define LAS __attribute__((address_space(3)))
; __device__ __forceinline__ void attn_unit(LAS unsigned char* lds, const bf16* PROJ, bf16* DA, const float* sinkl, int unit, int tid, int wid, int lane) {
;     ...
;     for (int hp = 0; hp < 2; ++hp) {
;         v4u kreg[3], vreg[3];
; #pragma unroll
;         for (int i = 0; i < 3; ++i) {
;             const int idx = tid + 512 * (3 * hp + i), c = idx >> 3, ch = idx & 7, s = s0 + c;
;             if (s >= 0 && s < SEQ) { const bf16* p = PROJ + (rowb + s) * INW + 1024 + hk * 64 + ch * 8; kreg[i] = *(const v4u*)p; vreg[i] = *(const v4u*)(p + 128); }
;             else { kreg[i] = (v4u){0u, 0u, 0u, 0u}; vreg[i] = (v4u){0u, 0u, 0u, 0u}; }
;         }
; #pragma unroll
;         for (int i = 0; i < 3; ++i) {
;             const int idx = tid + 512 * (3 * hp + i), c = idx >> 3, ch = idx & 7;
;             *(LAS v4u*)(Ks + c * KS_PITCH + ch * 8) = kreg[i];
;             LAS bf16* vp = Vt + (ch * 8) * VT_PITCH + c;
;             vp[0 * VT_PITCH] = (bf16)(vreg[i].x & 0xffffu); vp[1 * VT_PITCH] = (bf16)(vreg[i].x >> 16);
;             vp[2 * VT_PITCH] = (bf16)(vreg[i].y & 0xffffu); vp[3 * VT_PITCH] = (bf16)(vreg[i].y >> 16);
;             vp[4 * VT_PITCH] = (bf16)(vreg[i].z & 0xffffu); vp[5 * VT_PITCH] = (bf16)(vreg[i].z >> 16);
;             vp[6 * VT_PITCH] = (bf16)(vreg[i].w & 0xffffu); vp[7 * VT_PITCH] = (bf16)(vreg[i].w >> 16);
;         }
.LBB0_355:
	s_and_b64 vcc, exec, s[36:37]
	s_cbranch_vccz .LBB0_423
	v_lshlrev_b32_e32 v2, 3, v173
	v_ashrrev_i32_e32 v42, 3, v173
	v_readlane_b32 s13, v239, 10
	v_and_b32_e32 v41, 56, v2
	v_lshlrev_b32_e32 v38, 1, v41
	v_mov_b32_e32 v39, v66
	s_waitcnt lgkmcnt(0)
	v_readlane_b32 s6, v239, 6
	v_readlane_b32 s7, v239, 7
	v_readlane_b32 s12, v239, 9
	s_lshl_b64 s[24:25], s[70:71], 2
	v_readlane_b32 s32, v239, 11
	s_add_u32 s24, s32, s24
	v_readlane_b32 s32, v239, 12
	s_addc_u32 s25, s32, s25
	v_readlane_b32 s88, v238, 7
	v_readlane_b32 s89, v238, 8
	v_bfe_u32 v189, v173, 5, 1
	v_lshlrev_b32_e32 v192, 4, v189
	v_mov_b32_e32 v193, v66
	v_lshl_add_u64 v[192:193], s[88:89], 0, v[192:193]
	v_and_b32_e32 v189, 31, v173
	v_or_b32_e32 v189, s80, v189
	v_or_b32_e32 v189, s12, v189
	v_or_b32_e32 v189, s6, v189
	v_mad_u64_u32 v[192:193], s[88:89], v189, s82, v[192:193]
	v_mad_i32_i24 v193, s7, v201, v193
	global_load_dwordx4 v[68:71], v[192:193], off offset:1024
	global_load_dwordx4 v[72:75], v[192:193], off offset:1056
	global_load_dwordx4 v[76:79], v[192:193], off offset:1088
	global_load_dwordx4 v[80:83], v[192:193], off offset:1120
	global_load_dword v191, v66, s[24:25]
	v_readlane_b32 s72, v238, 5
	v_readlane_b32 s73, v238, 6
	s_movk_i32 s84, 0x1000
	v_add_u32_e32 v2, 0x200, v173
	v_ashrrev_i32_e32 v43, 3, v2
	v_add_u32_e32 v2, 0x400, v173
	v_ashrrev_i32_e32 v44, 3, v2
	v_add_u32_e32 v2, 0x600, v173
	v_ashrrev_i32_e32 v186, 3, v2
	v_add_u32_e32 v2, 0x800, v173
	v_ashrrev_i32_e32 v187, 3, v2
	v_add_u32_e32 v2, 0xa00, v173
	v_ashrrev_i32_e32 v188, 3, v2
	v_add_u32_e32 v189, s13, v42
	v_cmp_gt_u32_e64 s[28:29], s84, v189
	v_and_b32_e32 v189, 0xfff, v189
	v_or_b32_e32 v190, s6, v189
	v_mov_b64_e32 v[192:193], s[72:73]
	v_mad_u64_u32 v[192:193], s[88:89], v190, s82, v[192:193]
	v_mad_i32_i24 v193, s7, v201, v193
	v_lshl_add_u64 v[192:193], v[192:193], 0, v[38:39]
	global_load_dwordx4 v[26:29], v[192:193], off offset:2048
	global_load_dwordx4 v[174:177], v[192:193], off offset:2304
	v_add_u32_e32 v189, s13, v43
	v_cmp_gt_u32_e64 s[30:31], s84, v189
	v_and_b32_e32 v189, 0xfff, v189
	v_or_b32_e32 v190, s6, v189
	v_mov_b64_e32 v[192:193], s[72:73]
	v_mad_u64_u32 v[192:193], s[88:89], v190, s82, v[192:193]
	v_mad_i32_i24 v193, s7, v201, v193
	v_lshl_add_u64 v[192:193], v[192:193], 0, v[38:39]
	global_load_dwordx4 v[30:33], v[192:193], off offset:2048
	global_load_dwordx4 v[178:181], v[192:193], off offset:2304
	v_add_u32_e32 v189, s13, v44
	v_cmp_gt_u32_e64 s[34:35], s84, v189
	v_and_b32_e32 v189, 0xfff, v189
	v_or_b32_e32 v190, s6, v189
	v_mov_b64_e32 v[192:193], s[72:73]
	v_mad_u64_u32 v[192:193], s[88:89], v190, s82, v[192:193]
	v_mad_i32_i24 v193, s7, v201, v193
	v_lshl_add_u64 v[192:193], v[192:193], 0, v[38:39]
	global_load_dwordx4 v[34:37], v[192:193], off offset:2048
	global_load_dwordx4 v[182:185], v[192:193], off offset:2304
	v_add_u32_e32 v189, s13, v186
	v_cmp_gt_u32_e64 s[62:63], s84, v189
	v_and_b32_e32 v189, 0xfff, v189
	v_or_b32_e32 v190, s6, v189
	v_mov_b64_e32 v[192:193], s[72:73]
	v_mad_u64_u32 v[192:193], s[88:89], v190, s82, v[192:193]
	v_mad_i32_i24 v193, s7, v201, v193
	v_lshl_add_u64 v[192:193], v[192:193], 0, v[38:39]
	global_load_dwordx4 v[6:9], v[192:193], off offset:2048
	global_load_dwordx4 v[2:5], v[192:193], off offset:2304
	v_add_u32_e32 v189, s13, v187
	v_cmp_gt_u32_e64 s[74:75], s84, v189
	v_and_b32_e32 v189, 0xfff, v189
	v_or_b32_e32 v190, s6, v189
	v_mov_b64_e32 v[192:193], s[72:73]
	v_mad_u64_u32 v[192:193], s[88:89], v190, s82, v[192:193]
	v_mad_i32_i24 v193, s7, v201, v193
	v_lshl_add_u64 v[192:193], v[192:193], 0, v[38:39]
	global_load_dwordx4 v[14:17], v[192:193], off offset:2048
	global_load_dwordx4 v[10:13], v[192:193], off offset:2304
	v_add_u32_e32 v189, s13, v188
	v_cmp_gt_u32_e64 s[76:77], s84, v189
	v_and_b32_e32 v189, 0xfff, v189
	v_or_b32_e32 v190, s6, v189
	v_mov_b64_e32 v[192:193], s[72:73]
	v_mad_u64_u32 v[192:193], s[88:89], v190, s82, v[192:193]
	v_mad_i32_i24 v193, s7, v201, v193
	v_lshl_add_u64 v[192:193], v[192:193], 0, v[38:39]
	global_load_dwordx4 v[22:25], v[192:193], off offset:2048
	global_load_dwordx4 v[18:21], v[192:193], off offset:2304
	v_lshl_add_u32 v40, v41, 1, 0
	s_movk_i32 s32, 0x306
	v_mad_u32_u24 v41, v41, s32, v40
	s_waitcnt vmcnt(11)
	v_cndmask_b32_e64 v26, 0, v26, s[28:29]
	v_cndmask_b32_e64 v27, 0, v27, s[28:29]
	v_cndmask_b32_e64 v28, 0, v28, s[28:29]
	v_cndmask_b32_e64 v29, 0, v29, s[28:29]
	v_mad_u32_u24 v121, v42, s3, v40
	ds_write_b128 v121, v[26:29]
	s_waitcnt vmcnt(10)
	v_cndmask_b32_e64 v174, 0, v174, s[28:29]
	v_cndmask_b32_e64 v175, 0, v175, s[28:29]
	v_cndmask_b32_e64 v176, 0, v176, s[28:29]
	v_cndmask_b32_e64 v177, 0, v177, s[28:29]
	v_lshl_add_u32 v122, v42, 1, v41
	ds_write_b16 v122, v174 offset:55296
	ds_write_b16_d16_hi v122, v174 offset:56072
	ds_write_b16 v122, v175 offset:56848
	ds_write_b16_d16_hi v122, v175 offset:57624
	ds_write_b16 v122, v176 offset:58400
	ds_write_b16_d16_hi v122, v176 offset:59176
	ds_write_b16 v122, v177 offset:59952
	ds_write_b16_d16_hi v122, v177 offset:60728
	s_waitcnt vmcnt(9)
	v_cndmask_b32_e64 v30, 0, v30, s[30:31]
	v_cndmask_b32_e64 v31, 0, v31, s[30:31]
	v_cndmask_b32_e64 v32, 0, v32, s[30:31]
	v_cndmask_b32_e64 v33, 0, v33, s[30:31]
	v_mad_u32_u24 v121, v43, s3, v40
	ds_write_b128 v121, v[30:33]
	s_waitcnt vmcnt(8)
; #define LAS __attribute__((address_space(3)))
; __device__ __forceinline__ void attn_unit(LAS unsigned char* lds, const bf16* PROJ, bf16* DA, const float* sinkl, int unit, int tid, int wid, int lane) {
;     ...
; #pragma unroll
;         for (int i = 0; i < 3; ++i) {
;             const int idx = tid + 512 * (3 * hp + i), c = idx >> 3, ch = idx & 7;
;             *(LAS v4u*)(Ks + c * KS_PITCH + ch * 8) = kreg[i];
;             LAS bf16* vp = Vt + (ch * 8) * VT_PITCH + c;
;             vp[0 * VT_PITCH] = (bf16)(vreg[i].x & 0xffffu); vp[1 * VT_PITCH] = (bf16)(vreg[i].x >> 16);
;             vp[2 * VT_PITCH] = (bf16)(vreg[i].y & 0xffffu); vp[3 * VT_PITCH] = (bf16)(vreg[i].y >> 16);
;             vp[4 * VT_PITCH] = (bf16)(vreg[i].z & 0xffffu); vp[5 * VT_PITCH] = (bf16)(vreg[i].z >> 16);
;             vp[6 * VT_PITCH] = (bf16)(vreg[i].w & 0xffffu); vp[7 * VT_PITCH] = (bf16)(vreg[i].w >> 16);
;         }
;     }
;     __syncthreads();
;     const int r32 = lane & 31, hi = lane >> 5;
;     const int hq = hk * 4 + (wid >> 1);
;     const float slope2 = __builtin_amdgcn_exp2f(-(float)(hq + 1)) * LOG2E;
;     const float sink2 = sinkl[hq] * LOG2E;
;     const float NEG = -INFINITY;
;     const bool edge_n = (n == 0) || (n == 31);
; #pragma unroll 1
;     for (int sb = 0; sb < 2; ++sb) {
;         const int a0 = 64 * (wid & 1) + 32 * sb, a = a0 + r32;
;         const size_t qrow = rowb + (size_t)n * 128 + a;
;         bf16x8 qf[4];
; #pragma unroll
;         for (int ks = 0; ks < 4; ++ks) qf[ks] = *(const bf16x8*)(PROJ + qrow * INW + 512 + hq * 64 + ks * 16 + hi * 8);
;         float mrun = sink2, l = 0.f;
;         f32x16 o0, o1;
; #pragma unroll
;         for (int r = 0; r < 16; ++r) { o0[r] = 0.f; o1[r] = 0.f; }
;         const float fb0 = (float)(r32 + 128 - 4 * hi);
	v_cndmask_b32_e64 v178, 0, v178, s[30:31]
	v_cndmask_b32_e64 v179, 0, v179, s[30:31]
	v_cndmask_b32_e64 v180, 0, v180, s[30:31]
	v_cndmask_b32_e64 v181, 0, v181, s[30:31]
	v_lshl_add_u32 v122, v43, 1, v41
	ds_write_b16 v122, v178 offset:55296
	ds_write_b16_d16_hi v122, v178 offset:56072
	ds_write_b16 v122, v179 offset:56848
	ds_write_b16_d16_hi v122, v179 offset:57624
	ds_write_b16 v122, v180 offset:58400
	ds_write_b16_d16_hi v122, v180 offset:59176
	ds_write_b16 v122, v181 offset:59952
	ds_write_b16_d16_hi v122, v181 offset:60728
	s_waitcnt vmcnt(7)
	v_cndmask_b32_e64 v34, 0, v34, s[34:35]
	v_cndmask_b32_e64 v35, 0, v35, s[34:35]
	v_cndmask_b32_e64 v36, 0, v36, s[34:35]
	v_cndmask_b32_e64 v37, 0, v37, s[34:35]
	v_mad_u32_u24 v121, v44, s3, v40
	ds_write_b128 v121, v[34:37]
	s_waitcnt vmcnt(6)
	v_cndmask_b32_e64 v182, 0, v182, s[34:35]
	v_cndmask_b32_e64 v183, 0, v183, s[34:35]
	v_cndmask_b32_e64 v184, 0, v184, s[34:35]
	v_cndmask_b32_e64 v185, 0, v185, s[34:35]
	v_lshl_add_u32 v122, v44, 1, v41
	ds_write_b16 v122, v182 offset:55296
	ds_write_b16_d16_hi v122, v182 offset:56072
	ds_write_b16 v122, v183 offset:56848
	ds_write_b16_d16_hi v122, v183 offset:57624
	ds_write_b16 v122, v184 offset:58400
	ds_write_b16_d16_hi v122, v184 offset:59176
	ds_write_b16 v122, v185 offset:59952
	ds_write_b16_d16_hi v122, v185 offset:60728
	s_waitcnt vmcnt(5)
	v_cndmask_b32_e64 v6, 0, v6, s[62:63]
	v_cndmask_b32_e64 v7, 0, v7, s[62:63]
	v_cndmask_b32_e64 v8, 0, v8, s[62:63]
	v_cndmask_b32_e64 v9, 0, v9, s[62:63]
	v_mad_u32_u24 v121, v186, s3, v40
	ds_write_b128 v121, v[6:9]
	s_waitcnt vmcnt(4)
	v_cndmask_b32_e64 v2, 0, v2, s[62:63]
	v_cndmask_b32_e64 v3, 0, v3, s[62:63]
	v_cndmask_b32_e64 v4, 0, v4, s[62:63]
	v_cndmask_b32_e64 v5, 0, v5, s[62:63]
	v_lshl_add_u32 v122, v186, 1, v41
	ds_write_b16 v122, v2 offset:55296
	ds_write_b16_d16_hi v122, v2 offset:56072
	ds_write_b16 v122, v3 offset:56848
	ds_write_b16_d16_hi v122, v3 offset:57624
	ds_write_b16 v122, v4 offset:58400
	ds_write_b16_d16_hi v122, v4 offset:59176
	ds_write_b16 v122, v5 offset:59952
	ds_write_b16_d16_hi v122, v5 offset:60728
	s_waitcnt vmcnt(3)
	v_cndmask_b32_e64 v14, 0, v14, s[74:75]
	v_cndmask_b32_e64 v15, 0, v15, s[74:75]
	v_cndmask_b32_e64 v16, 0, v16, s[74:75]
	v_cndmask_b32_e64 v17, 0, v17, s[74:75]
	v_mad_u32_u24 v121, v187, s3, v40
	ds_write_b128 v121, v[14:17]
	s_waitcnt vmcnt(2)
	v_cndmask_b32_e64 v10, 0, v10, s[74:75]
	v_cndmask_b32_e64 v11, 0, v11, s[74:75]
	v_cndmask_b32_e64 v12, 0, v12, s[74:75]
	v_cndmask_b32_e64 v13, 0, v13, s[74:75]
	v_lshl_add_u32 v122, v187, 1, v41
	ds_write_b16 v122, v10 offset:55296
	ds_write_b16_d16_hi v122, v10 offset:56072
	ds_write_b16 v122, v11 offset:56848
	ds_write_b16_d16_hi v122, v11 offset:57624
	ds_write_b16 v122, v12 offset:58400
	ds_write_b16_d16_hi v122, v12 offset:59176
	ds_write_b16 v122, v13 offset:59952
	ds_write_b16_d16_hi v122, v13 offset:60728
	s_waitcnt vmcnt(1)
	v_cndmask_b32_e64 v22, 0, v22, s[76:77]
	v_cndmask_b32_e64 v23, 0, v23, s[76:77]
	v_cndmask_b32_e64 v24, 0, v24, s[76:77]
	v_cndmask_b32_e64 v25, 0, v25, s[76:77]
	v_mad_u32_u24 v121, v188, s3, v40
	ds_write_b128 v121, v[22:25]
	s_waitcnt vmcnt(0)
	v_cndmask_b32_e64 v18, 0, v18, s[76:77]
	v_cndmask_b32_e64 v19, 0, v19, s[76:77]
	v_cndmask_b32_e64 v20, 0, v20, s[76:77]
	v_cndmask_b32_e64 v21, 0, v21, s[76:77]
	v_lshl_add_u32 v122, v188, 1, v41
	ds_write_b16 v122, v18 offset:55296
	ds_write_b16_d16_hi v122, v18 offset:56072
	ds_write_b16 v122, v19 offset:56848
	ds_write_b16_d16_hi v122, v19 offset:57624
	ds_write_b16 v122, v20 offset:58400
	ds_write_b16_d16_hi v122, v20 offset:59176
	ds_write_b16 v122, v21 offset:59952
	ds_write_b16_d16_hi v122, v21 offset:60728
	s_waitcnt lgkmcnt(0)
	s_barrier
	v_mul_f32_e32 v204, 0x00000000, v162
	v_mul_f32_e32 v205, 0x3f800000, v162
	v_mul_f32_e32 v206, 0x40000000, v162
	v_mul_f32_e32 v207, 0x40400000, v162
	v_mul_f32_e32 v208, 0x41000000, v162
	v_mul_f32_e32 v209, 0x41100000, v162
	v_mul_f32_e32 v210, 0x41200000, v162
	v_mul_f32_e32 v211, 0x41300000, v162
	v_mul_f32_e32 v212, 0x41800000, v162
	v_mul_f32_e32 v213, 0x41880000, v162
	v_mul_f32_e32 v214, 0x41900000, v162
	v_mul_f32_e32 v215, 0x41980000, v162
	v_mul_f32_e32 v216, 0x41c00000, v162
	v_mul_f32_e32 v217, 0x41c80000, v162
	v_mul_f32_e32 v218, 0x41d00000, v162
	v_mul_f32_e32 v219, 0x41d80000, v162
	v_mul_f32_e32 v220, 0x80000000, v162
	v_mul_f32_e32 v221, 0xbf800000, v162
	v_mul_f32_e32 v222, 0xc0000000, v162
	v_mul_f32_e32 v223, 0xc0400000, v162
	v_mul_f32_e32 v224, 0xc1000000, v162
	v_mul_f32_e32 v225, 0xc1100000, v162
	v_mul_f32_e32 v226, 0xc1200000, v162
	v_mul_f32_e32 v227, 0xc1300000, v162
	v_mul_f32_e32 v228, 0xc1800000, v162
	v_mul_f32_e32 v229, 0xc1880000, v162
	v_mul_f32_e32 v230, 0xc1900000, v162
	v_mul_f32_e32 v231, 0xc1980000, v162
	v_mul_f32_e32 v232, 0xc1c00000, v162
	v_mul_f32_e32 v233, 0xc1c80000, v162
	v_mul_f32_e32 v234, 0xc1d00000, v162
	v_mul_f32_e32 v235, 0xc1d80000, v162
	v_and_b32_e32 v67, 63, v173
	v_bfe_u32 v2, v173, 5, 1
	v_readlane_b32 s24, v238, 7
	v_and_b32_e32 v85, 31, v173
	v_lshlrev_b32_e32 v4, 3, v2
	v_lshlrev_b32_e32 v5, 2, v2
	v_lshlrev_b32_e32 v2, 4, v2
	v_or_b32_e32 v6, 32, v67
	v_readlane_b32 s25, v238, 8
	v_mul_u32_u24_e32 v7, 0x308, v85
	v_mul_u32_u24_e32 v8, 0x308, v6
	v_readlane_b32 s13, v238, 15
	v_add_u32_e32 v84, 0, v2
	v_sub_u32_e32 v95, v85, v5
	v_add3_u32 v96, v8, v4, s13
	v_add3_u32 v97, v7, v4, s13
	v_readlane_b32 s13, v238, 19
	v_add_u32_e32 v99, s80, v6
	s_mov_b32 s36, 0
	v_sub_u32_e32 v98, s13, v5
	s_mov_b64 s[38:39], -1
	s_mov_b32 s23, 0
	v_mul_f32_e32 v94, 0x3fb8aa3b, v191
	v_mov_b32_e32 v3, v66
	v_lshl_add_u64 v[86:87], s[24:25], 0, v[2:3]
	v_readlane_b32 s24, v238, 9
	v_readlane_b32 s25, v238, 10
	s_nop 1
	v_lshl_add_u64 v[88:89], s[24:25], 0, v[2:3]
	s_branch .LBB0_380

; #define ATT_QK(dst, cblk) do { _Pragma("unroll") for (int r = 0; r < 16; ++r) dst[r] = 0.f; \
;             _Pragma("unroll") for (int ks = 0; ks < 4; ++ks) { const bf16x8 kf = *(const LAS bf16x8*)(Ks + ((cblk) + r32) * KS_PITCH + ks * 16 + hi * 8); \
;                 dst = __builtin_amdgcn_mfma_f32_32x32x16_bf16(kf, qf[ks], dst, 0, 0, 0); } } while (0)
; __device__ __forceinline__ void attn_unit(LAS unsigned char* lds, const bf16* PROJ, bf16* DA, const float* sinkl, int unit, int tid, int wid, int lane) {
;     ...
;         const float fb0 = (float)(r32 + 128 - 4 * hi);
;         f32x16 pn;
;     ...
;         ATT_QK(pn, a0);
.Lq_skip1:
	v_mad_u32_u24 v26, v4, s3, v84
	ds_read_b128 v[18:21], v26
	ds_read_b128 v[22:25], v26 offset:32
	s_mov_b32 s37, s36
	s_xor_b64 s[70:71], s[38:39], -1
	s_mov_b32 s38, s36
	s_mov_b32 s39, s36
	s_mov_b32 s40, s36
	s_mov_b32 s41, s36
	s_mov_b32 s42, s36
	s_mov_b32 s43, s36
	s_mov_b32 s44, s36
	s_mov_b32 s45, s36
	s_mov_b32 s46, s36
	s_mov_b32 s47, s36
	s_mov_b32 s48, s36
	s_mov_b32 s49, s36
	s_mov_b32 s50, s36
	s_mov_b32 s51, s36
	v_mov_b64_e32 v[2:3], s[36:37]
	v_mov_b64_e32 v[16:17], s[50:51]
	s_lshl_b32 s24, s23, 1
	v_mov_b64_e32 v[4:5], s[38:39]
	v_mov_b64_e32 v[6:7], s[40:41]
	v_mov_b64_e32 v[8:9], s[42:43]
	v_mov_b64_e32 v[10:11], s[44:45]
	v_mov_b64_e32 v[12:13], s[46:47]
	v_mov_b64_e32 v[14:15], s[48:49]
	v_add_u32_e32 v100, s24, v96
	v_add_u32_e32 v101, s24, v97
	v_mov_b32_e32 v91, s7
	v_subrev_u32_e32 v102, s23, v98
	v_mov_b32_e32 v103, v94
	s_waitcnt vmcnt(3) lgkmcnt(1)
	v_mfma_f32_32x32x16_bf16 v[50:65], v[18:21], v[68:71], v[204:219]
	ds_read_b128 v[18:21], v26 offset:64
	s_waitcnt vmcnt(2) lgkmcnt(1)
	v_mfma_f32_32x32x16_bf16 v[50:65], v[22:25], v[72:75], v[50:65]
	s_waitcnt vmcnt(1) lgkmcnt(0)
	v_mfma_f32_32x32x16_bf16 v[50:65], v[18:21], v[76:79], v[50:65]
	ds_read_b128 v[18:21], v26 offset:96
	s_waitcnt vmcnt(0) lgkmcnt(0)
	v_mfma_f32_32x32x16_bf16 v[50:65], v[18:21], v[80:83], v[50:65]
	v_add_u32_e32 v18, s23, v99
	v_mad_u64_u32 v[92:93], s[24:25], v18, s3, v[84:85]
	v_mov_b64_e32 v[32:33], v[16:17]
	v_mov_b32_e32 v93, 0
	s_mov_b32 s23, 0
	s_mov_b32 s24, 0
	s_nop 5
	v_mov_b64_e32 v[34:35], v[50:51]
	v_mov_b64_e32 v[30:31], v[14:15]
	v_mov_b64_e32 v[28:29], v[12:13]
	v_mov_b64_e32 v[26:27], v[10:11]
	v_mov_b64_e32 v[24:25], v[8:9]
	v_mov_b64_e32 v[22:23], v[6:7]
	v_mov_b64_e32 v[20:21], v[4:5]
	v_mov_b64_e32 v[18:19], v[2:3]
	v_mov_b64_e32 v[36:37], v[52:53]
	v_mov_b64_e32 v[38:39], v[54:55]
	v_mov_b64_e32 v[40:41], v[56:57]
	v_mov_b64_e32 v[42:43], v[58:59]
	v_mov_b64_e32 v[44:45], v[60:61]
	v_mov_b64_e32 v[46:47], v[62:63]
	v_mov_b64_e32 v[48:49], v[64:65]

; __device__ __forceinline__ void attn_unit(LAS unsigned char* lds, const bf16* PROJ, bf16* DA, const float* sinkl, int unit, int tid, int wid, int lane) {
;     ...
;             const float fb = fb0 - (float)(32 * i);
;             const int sb0 = s0 + c0 + 4 * hi;
;             const float kmin = fmaxf(fb - 128.0f, (float)(-sb0)), kmax = fminf(fb + 128.0f, (float)(SEQ - 1 - sb0));
;             const float kmid = 0.5f * (kmin + kmax), khw = 0.5f * (kmax - kmin);
;             float mx = NEG;
; #pragma unroll
;             for (int r = 0; r < 16; ++r) { const float kr = (float)((r & 3) + 8 * (r >> 2)); p[r] = p[r] - slope2 * fabsf(fb - kr); }
.LBB0_382:
	v_add_u32_e32 v105, s23, v95
	v_add_u32_e32 v104, 0x80, v105
	v_cvt_f32_i32_e32 v104, v104
	s_cmp_eq_u32 s23, 0xffffff80
	s_cbranch_scc1 .Lalibi_mixed
	v_mul_f32_e32 v146, v162, v104
	s_cmp_gt_i32 s23, 0xffffff80
	s_cbranch_scc0 .Lalibi_neg
	s_branch .Lalibi_done
.Lalibi_neg:
	v_xor_b32_e32 v146, 0x80000000, v146
	s_branch .Lalibi_done

; #define ATT_QK(dst, cblk) do { _Pragma("unroll") for (int r = 0; r < 16; ++r) dst[r] = 0.f; \
;             _Pragma("unroll") for (int ks = 0; ks < 4; ++ks) { const bf16x8 kf = *(const LAS bf16x8*)(Ks + ((cblk) + r32) * KS_PITCH + ks * 16 + hi * 8); \
;                 dst = __builtin_amdgcn_mfma_f32_32x32x16_bf16(kf, qf[ks], dst, 0, 0, 0); } } while (0)
; __device__ __forceinline__ void attn_unit(LAS unsigned char* lds, const bf16* PROJ, bf16* DA, const float* sinkl, int unit, int tid, int wid, int lane) {
;     ...
;             if (i < 8) ATT_QK(pn, c0 + 32);
;     ...
;             if ((i == 0) || (i == 8) || edge_n) {
.Lalibi_done:
	s_and_b32 s25, s24, 7
	s_cmp_eq_u32 s25, 0
	s_cbranch_scc1 .LBB0_391
	s_cmp_gt_i32 s78, 30
	s_mov_b64 s[38:39], -1
	s_cbranch_scc1 .LBB0_385
	s_cmp_eq_u32 s78, 0
	s_cselect_b64 s[38:39], -1, 0

; #define LAS __attribute__((address_space(3)))
; __device__ __forceinline__ void attn_unit(LAS unsigned char* lds, const bf16* PROJ, bf16* DA, const float* sinkl, int unit, int tid, int wid, int lane) {
;     ...
;             if (i < 8) ATT_QK(pn, c0 + 32);
;             const float fb = fb0 - (float)(32 * i);
;             const int sb0 = s0 + c0 + 4 * hi;
;             const float kmin = fmaxf(fb - 128.0f, (float)(-sb0)), kmax = fminf(fb + 128.0f, (float)(SEQ - 1 - sb0));
;             const float kmid = 0.5f * (kmin + kmax), khw = 0.5f * (kmax - kmin);
;             float mx = NEG;
; #pragma unroll
;             for (int r = 0; r < 16; ++r) { const float kr = (float)((r & 3) + 8 * (r >> 2)); p[r] = p[r] - slope2 * fabsf(fb - kr); }
;             if ((i == 0) || (i == 8) || edge_n) {
; #pragma unroll
;                 for (int r = 0; r < 16; ++r) { const float kr = (float)((r & 3) + 8 * (r >> 2)); p[r] = (fabsf(kr - kmid) <= khw) ? p[r] : NEG; }
;             }
; #pragma unroll
;             for (int r = 0; r < 16; ++r) mx = fmaxf(mx, p[r]);
;             { const auto rr = __builtin_amdgcn_permlane32_swap(__float_as_uint(mx), __float_as_uint(mx), false, false); mx = fmaxf(__uint_as_float(rr[0]), __uint_as_float(rr[1])); }
;             if (__any(mx > mrun + 8.0f)) {
;                 const float mnew = fmaxf(mrun, mx), alpha = __builtin_amdgcn_exp2f(mrun - mnew);
;                 mrun = mnew; l *= alpha;
; #pragma unroll
;                 for (int r = 0; r < 16; ++r) { o0[r] *= alpha; o1[r] *= alpha; }
;             }
;             float ps = 0.f;
; #pragma unroll
;             for (int r = 0; r < 16; ++r) { p[r] = __builtin_amdgcn_exp2f(p[r] - mrun); ps += p[r]; }
;             l += ps;
; #pragma unroll
;             for (int s = 0; s < 2; ++s) {
;                 v4u pw; pw.x = pg8::cvt_pk_bf16(p[8 * s + 0], p[8 * s + 1]); pw.y = pg8::cvt_pk_bf16(p[8 * s + 2], p[8 * s + 3]);
;                 pw.z = pg8::cvt_pk_bf16(p[8 * s + 4], p[8 * s + 5]); pw.w = pg8::cvt_pk_bf16(p[8 * s + 6], p[8 * s + 7]);
;                 const bf16x8 pb = __builtin_bit_cast(bf16x8, pw);
; #pragma unroll
;                 for (int db = 0; db < 2; ++db) {
;                     const LAS bf16* vp = Vt + (db * 32 + r32) * VT_PITCH + c0 + 16 * s + 4 * hi;
;                     const s16x4 vlo = *(const LAS s16x4*)vp, vhi = *(const LAS s16x4*)(vp + 8);
.LBB0_387:
	v_max3_f32 v104, v50, s22, v51
	v_max3_f32 v104, v104, v52, v53
	v_max3_f32 v104, v104, v54, v55
	v_max3_f32 v104, v104, v56, v57
	v_max3_f32 v104, v104, v58, v59
	v_max3_f32 v104, v104, v60, v61
	v_max3_f32 v104, v104, v62, v63
	v_max3_f32 v104, v104, v64, v65
	v_mov_b32_e32 v105, v104
	s_nop 1
	v_permlane32_swap_b32_e32 v104, v105
	v_max_f32_e32 v105, v105, v105
	v_max_f32_e32 v104, v104, v104
	v_max_f32_e32 v104, v104, v105
	v_sub_f32_e32 v104, v104, v146
	v_add_f32_e32 v105, 0x41000000, v103
	v_cmp_gt_f32_e32 vcc, v104, v105
	s_cbranch_vccz .LBB0_389
	v_max_f32_e32 v104, v104, v104
	v_max_f32_e32 v105, v103, v103
	v_max_f32_e32 v105, v105, v104
	v_sub_f32_e32 v103, v103, v105
	v_exp_f32_e32 v104, v103
	v_mov_b32_e32 v103, v105
	v_pk_mul_f32 v[32:33], v[32:33], v[104:105] op_sel_hi:[1,0]
	v_pk_mul_f32 v[30:31], v[30:31], v[104:105] op_sel_hi:[1,0]
	v_pk_mul_f32 v[28:29], v[28:29], v[104:105] op_sel_hi:[1,0]
	v_pk_mul_f32 v[26:27], v[26:27], v[104:105] op_sel_hi:[1,0]
	v_pk_mul_f32 v[24:25], v[24:25], v[104:105] op_sel_hi:[1,0]
	v_pk_mul_f32 v[22:23], v[22:23], v[104:105] op_sel_hi:[1,0]
	v_pk_mul_f32 v[20:21], v[20:21], v[104:105] op_sel_hi:[1,0]
	v_pk_mul_f32 v[18:19], v[18:19], v[104:105] op_sel_hi:[1,0]
	v_pk_mul_f32 v[16:17], v[16:17], v[104:105] op_sel_hi:[1,0]
	v_pk_mul_f32 v[14:15], v[14:15], v[104:105] op_sel_hi:[1,0]
	v_pk_mul_f32 v[12:13], v[12:13], v[104:105] op_sel_hi:[1,0]
	v_pk_mul_f32 v[10:11], v[10:11], v[104:105] op_sel_hi:[1,0]
	v_pk_mul_f32 v[8:9], v[8:9], v[104:105] op_sel_hi:[1,0]
	v_pk_mul_f32 v[6:7], v[6:7], v[104:105] op_sel_hi:[1,0]
	v_pk_mul_f32 v[4:5], v[4:5], v[104:105] op_sel_hi:[1,0]
	v_pk_mul_f32 v[2:3], v[2:3], v[104:105] op_sel_hi:[1,0]
	v_mul_f32_e32 v93, v93, v104
.LBB0_389:
	v_add_f32_e32 v148, v103, v146
	ds_read2_b64 v[122:125], v101 offset1:2
	ds_read2_b64 v[126:129], v100 offset1:2
	ds_read2_b64 v[130:133], v101 offset0:4 offset1:6
	ds_read2_b64 v[134:137], v100 offset0:4 offset1:6
	v_pk_add_f32 v[50:51], v[50:51], v[148:149] op_sel_hi:[1,0] neg_lo:[0,1] neg_hi:[0,1]
	v_pk_add_f32 v[52:53], v[52:53], v[148:149] op_sel_hi:[1,0] neg_lo:[0,1] neg_hi:[0,1]
	v_exp_f32_e32 v50, v50
	v_pk_add_f32 v[54:55], v[54:55], v[148:149] op_sel_hi:[1,0] neg_lo:[0,1] neg_hi:[0,1]
	v_exp_f32_e32 v51, v51
	v_pk_add_f32 v[56:57], v[56:57], v[148:149] op_sel_hi:[1,0] neg_lo:[0,1] neg_hi:[0,1]
	v_exp_f32_e32 v52, v52
	v_pk_add_f32 v[58:59], v[58:59], v[148:149] op_sel_hi:[1,0] neg_lo:[0,1] neg_hi:[0,1]
	v_exp_f32_e32 v53, v53
	v_pk_add_f32 v[60:61], v[60:61], v[148:149] op_sel_hi:[1,0] neg_lo:[0,1] neg_hi:[0,1]
	v_exp_f32_e32 v54, v54
	v_pk_add_f32 v[62:63], v[62:63], v[148:149] op_sel_hi:[1,0] neg_lo:[0,1] neg_hi:[0,1]
	v_exp_f32_e32 v55, v55
	v_pk_add_f32 v[64:65], v[64:65], v[148:149] op_sel_hi:[1,0] neg_lo:[0,1] neg_hi:[0,1]
	v_exp_f32_e32 v56, v56
	v_cvt_pk_bf16_f32 v150, v50, v51
	v_exp_f32_e32 v57, v57
	v_cvt_pk_bf16_f32 v151, v52, v53
	v_exp_f32_e32 v58, v58
	v_pk_add_f32 v[236:237], v[50:51], v[52:53]
	v_exp_f32_e32 v59, v59
	v_cvt_pk_bf16_f32 v152, v54, v55
	v_exp_f32_e32 v60, v60
	v_pk_add_f32 v[236:237], v[236:237], v[54:55]
	v_exp_f32_e32 v61, v61
	v_cvt_pk_bf16_f32 v153, v56, v57
	v_exp_f32_e32 v62, v62
	v_pk_add_f32 v[236:237], v[236:237], v[56:57]
	v_exp_f32_e32 v63, v63
	s_add_i32 s24, s24, 1
	s_sub_i32 s23, s23, 32
	s_waitcnt lgkmcnt(3)
	v_mfma_f32_32x32x16_bf16 v[18:33], v[122:125], v[150:153], v[18:33]
	v_exp_f32_e32 v64, v64
	v_cvt_pk_bf16_f32 v140, v58, v59
	v_exp_f32_e32 v65, v65
	v_cvt_pk_bf16_f32 v141, v60, v61
	v_pk_add_f32 v[236:237], v[236:237], v[58:59]
	s_waitcnt lgkmcnt(2)
	v_mfma_f32_32x32x16_bf16 v[2:17], v[126:129], v[150:153], v[2:17]
	v_cvt_pk_bf16_f32 v142, v62, v63
	v_pk_add_f32 v[236:237], v[236:237], v[60:61]
	v_cvt_pk_bf16_f32 v143, v64, v65
	v_pk_add_f32 v[236:237], v[236:237], v[62:63]
	v_pk_add_f32 v[236:237], v[236:237], v[64:65]
	v_add_u32_e32 v100, 64, v100
	s_waitcnt lgkmcnt(1)
	v_mfma_f32_32x32x16_bf16 v[18:33], v[130:133], v[140:143], v[18:33]
	v_add_u32_e32 v101, 64, v101
	v_add_f32_e32 v236, v236, v237
	s_waitcnt lgkmcnt(0)
	v_mfma_f32_32x32x16_bf16 v[2:17], v[134:137], v[140:143], v[2:17]
	v_add_f32_e32 v93, v93, v236
	s_cmpk_eq_i32 s23, 0xfee0
	v_add_u32_e32 v92, 0x1200, v92
	s_cbranch_scc1 .LBB0_379
	s_cmp_gt_i32 s23, 0xffffff80
	s_cbranch_scc1 .Lqa_pos
	s_cmp_eq_u32 s23, 0xffffff80
	s_cbranch_scc1 .Lqa_zero
	v_mfma_f32_32x32x16_bf16 v[50:65], v[174:177], v[68:71], v[220:235]
	s_branch .Lqa_done
.Lqa_zero:
	v_mfma_f32_32x32x16_bf16 v[50:65], v[174:177], v[68:71], 0
	s_branch .Lqa_done
.Lqa_pos:
	v_mfma_f32_32x32x16_bf16 v[50:65], v[174:177], v[68:71], v[204:219]
.Lqa_done:
	v_mfma_f32_32x32x16_bf16 v[50:65], v[178:181], v[72:75], v[50:65]
	v_mfma_f32_32x32x16_bf16 v[50:65], v[182:185], v[76:79], v[50:65]
	v_mfma_f32_32x32x16_bf16 v[50:65], v[186:189], v[80:83], v[50:65]
	s_nop 5
	s_branch .LBB0_381
